# SwiGLU GEMMs: lagging wave half re-establishes the stagger barrier after its own tile scheduling and accumulator zeroing (overlaps with the leading half) instead of before
# baseline (speedup 1.0000x reference)
; __device__ __forceinline__ int get_bid() { int b = blockIdx.x; asm volatile("" : "+s"(b)); return b; }
; __device__ __forceinline__ int xcd_remap(int L, int nwg) { const int q = nwg >> 3, r = nwg & 7, xcd = L & 7, off = L >> 3; return (xcd < r ? xcd * (q + 1) : r * (q + 1) + (xcd - r) * q) + off; }
;     __device__ __forceinline__ bool next(int i, Unit& u) const {
;         const int G = (int)gridDim.x; int vb = get_bid() + boff; vb = vb >= G ? vb - G : vb;
;         const int L = i * G + vb; if (L >= nwg) return false;
;         const int wgid = xcd_remap(L, nwg);
; template <class Epi, class Sched>
; __device__ __forceinline__ void gemm_phase(LAS unsigned char* lds, const int K, const int lda, const int ldb, const Sched& S, const Epi& E) {
;     ...
; #pragma unroll
;         for (int a = 0; a < 2; ++a)
; #pragma unroll
;             for (int b = 0; b < 2; ++b)
; #pragma unroll
;                 for (int m = 0; m < 4; ++m)
; #pragma unroll
;                     for (int n = 0; n < 2; ++n) acc[a][b][m][n] = (f32x4){0.f, 0.f, 0.f, 0.f};
;         cur = nxt; cA = nA; cB = nB; ++ui;
.LBB0_455:
	v_mov_b32_e32 v2, 0
	s_mov_b32 s4, s6
	s_mov_b32 s18, s75
	s_mov_b32 s54, s49
	v_mov_b32_e32 v3, v2
	v_mov_b64_e32 v[4:5], 0
	v_mov_b64_e32 v[6:7], 0
	v_mov_b64_e32 v[8:9], 0
	v_mov_b64_e32 v[10:11], 0
	v_mov_b64_e32 v[12:13], 0
	v_mov_b64_e32 v[14:15], 0
	v_mov_b64_e32 v[16:17], 0
	v_mov_b64_e32 v[18:19], 0
	v_mov_b64_e32 v[20:21], 0
	v_mov_b64_e32 v[22:23], 0
	v_mov_b64_e32 v[24:25], 0
	v_mov_b64_e32 v[26:27], 0
	v_mov_b64_e32 v[28:29], 0
	v_mov_b64_e32 v[30:31], 0
	v_mov_b64_e32 v[32:33], 0
	v_mov_b64_e32 v[34:35], 0
	v_mov_b64_e32 v[36:37], 0
	v_mov_b64_e32 v[38:39], 0
	v_mov_b64_e32 v[40:41], 0
	v_mov_b64_e32 v[42:43], 0
	v_mov_b64_e32 v[44:45], 0
	v_mov_b64_e32 v[46:47], 0
	v_mov_b64_e32 v[48:49], 0
	v_mov_b64_e32 v[50:51], 0
	v_mov_b64_e32 v[52:53], 0
	v_mov_b64_e32 v[54:55], 0
	v_mov_b64_e32 v[56:57], 0
	v_mov_b64_e32 v[58:59], 0
	v_mov_b64_e32 v[60:61], 0
	v_mov_b64_e32 v[62:63], 0
	v_mov_b64_e32 v[64:65], 0
	v_mov_b64_e32 v[66:67], 0
	v_mov_b64_e32 v[68:69], 0
	v_mov_b64_e32 v[70:71], 0
	v_mov_b64_e32 v[72:73], 0
	v_mov_b64_e32 v[74:75], 0
	v_mov_b64_e32 v[76:77], 0
	v_mov_b64_e32 v[78:79], 0
	v_mov_b64_e32 v[80:81], 0
	v_mov_b64_e32 v[82:83], 0
	v_mov_b64_e32 v[84:85], 0
	v_mov_b64_e32 v[86:87], 0
	v_mov_b64_e32 v[88:89], 0
	v_mov_b64_e32 v[90:91], 0
	v_mov_b64_e32 v[92:93], 0
	v_mov_b64_e32 v[94:95], 0
	v_mov_b64_e32 v[96:97], 0
	v_mov_b64_e32 v[98:99], 0
	v_mov_b64_e32 v[100:101], 0
	v_mov_b64_e32 v[102:103], 0
	v_mov_b64_e32 v[104:105], 0
	v_mov_b64_e32 v[106:107], 0
	v_mov_b64_e32 v[108:109], 0
	v_mov_b64_e32 v[110:111], 0
	v_mov_b64_e32 v[112:113], 0
	v_mov_b64_e32 v[114:115], 0
	v_mov_b64_e32 v[116:117], 0
	v_mov_b64_e32 v[118:119], 0
	v_mov_b64_e32 v[120:121], 0
	v_mov_b64_e32 v[122:123], 0
	v_mov_b64_e32 v[124:125], 0
	v_mov_b64_e32 v[126:127], 0
	v_mov_b64_e32 v[128:129], 0
	s_andn2_b64 vcc, exec, s[8:9]
	s_mov_b64 s[12:13], s[10:11]
	s_cbranch_vccz .LBB0_517
.LBB0_456:
	s_add_i32 s49, s54, 1
	s_mul_i32 s7, s49, s79
	s_mov_b32 s0, s74
	s_add_i32 s7, s7, s0
	s_cmp_lt_i32 s7, s78
	s_cselect_b64 s[14:15], -1, 0
	s_cmp_ge_i32 s7, s78
	s_cselect_b64 s[8:9], -1, 0
	s_and_b64 vcc, exec, s[8:9]
	s_cbranch_vccnz .LBB0_481
	s_and_b32 s6, s7, 7
	s_cmp_ge_u32 s6, s69
	s_mov_b64 s[0:1], -1
	s_cbranch_scc0 .LBB0_459
	s_sub_i32 s0, s6, s69
	s_mul_i32 s0, s0, s68
	s_add_i32 s10, s0, s89
	s_mov_b64 s[0:1], 0

; #define PG8_WAIT_V(n) asm volatile("s_waitcnt vmcnt(" #n ")" ::: "memory")
; #define PG8_BAR __builtin_amdgcn_s_barrier()
; template <class Epi, class Sched>
; __device__ __forceinline__ void gemm_phase(LAS unsigned char* lds, const int K, const int lda, const int ldb, const Sched& S, const Epi& E) {
;     ...
;     if (wr == 1) PG8_BAR;
;     PG8_WAIT_V(4); PG8_BAR;
.LBB0_483:
	s_cmpk_gt_u32 s88, 0xff
	s_cbranch_scc0 .Lgx_b_go
	s_cmp_eq_u32 s54, 0
	s_cbranch_scc1 .Lgx_b_go
	s_barrier

; #define PG8_BAR __builtin_amdgcn_s_barrier()
; template <class Epi, class Sched>
; __device__ __forceinline__ void gemm_phase(LAS unsigned char* lds, const int K, const int lda, const int ldb, const Sched& S, const Epi& E) {
;     ...
;     if (wr == 1) PG8_BAR;
;     ...
; #pragma unroll
;         for (int a = 0; a < 2; ++a)
; #pragma unroll
;             for (int b = 0; b < 2; ++b)
; #pragma unroll
;                 for (int m = 0; m < 4; ++m)
; #pragma unroll
;                     for (int n = 0; n < 2; ++n) acc[a][b][m][n] = (f32x4){0.f, 0.f, 0.f, 0.f};
;         cur = nxt; cA = nA; cB = nB; ++ui;
.LBB0_880:
	s_add_u32 s14, s14, 0x40080
	s_addc_u32 s15, s15, 0
	s_add_u32 s5, s16, 0x100
	v_mov_b32_e32 v2, 0
	s_addc_u32 s7, s17, 0
	s_mov_b32 s53, -2
	v_mov_b32_e32 v3, v2
	v_mov_b64_e32 v[4:5], 0
	v_mov_b64_e32 v[10:11], 0
	v_mov_b64_e32 v[12:13], 0
	v_mov_b64_e32 v[18:19], 0
	v_mov_b64_e32 v[20:21], 0
	v_mov_b64_e32 v[26:27], 0
	v_mov_b64_e32 v[28:29], 0
	v_mov_b64_e32 v[34:35], 0
	v_mov_b64_e32 v[36:37], 0
	v_mov_b64_e32 v[42:43], 0
	v_mov_b64_e32 v[44:45], 0
	v_mov_b64_e32 v[50:51], 0
	v_mov_b64_e32 v[52:53], 0
	v_mov_b64_e32 v[58:59], 0
	v_mov_b64_e32 v[60:61], 0
	v_mov_b64_e32 v[6:7], 0
	v_mov_b64_e32 v[8:9], 0
	v_mov_b64_e32 v[14:15], 0
	v_mov_b64_e32 v[16:17], 0
	v_mov_b64_e32 v[22:23], 0
	v_mov_b64_e32 v[24:25], 0
	v_mov_b64_e32 v[30:31], 0
	v_mov_b64_e32 v[32:33], 0
	v_mov_b64_e32 v[38:39], 0
	v_mov_b64_e32 v[40:41], 0
	v_mov_b64_e32 v[46:47], 0
	v_mov_b64_e32 v[48:49], 0
	v_mov_b64_e32 v[54:55], 0
	v_mov_b64_e32 v[56:57], 0
	v_mov_b64_e32 v[62:63], 0
	v_mov_b64_e32 v[64:65], 0
	v_mov_b64_e32 v[66:67], 0
	v_mov_b64_e32 v[68:69], 0
	v_mov_b64_e32 v[74:75], 0
	v_mov_b64_e32 v[76:77], 0
	v_mov_b64_e32 v[82:83], 0
	v_mov_b64_e32 v[84:85], 0
	v_mov_b64_e32 v[90:91], 0
	v_mov_b64_e32 v[92:93], 0
	v_mov_b64_e32 v[98:99], 0
	v_mov_b64_e32 v[100:101], 0
	v_mov_b64_e32 v[106:107], 0
	v_mov_b64_e32 v[108:109], 0
	v_mov_b64_e32 v[114:115], 0
	v_mov_b64_e32 v[116:117], 0
	v_mov_b64_e32 v[122:123], 0
	v_mov_b64_e32 v[124:125], 0
	v_mov_b64_e32 v[70:71], 0
	v_mov_b64_e32 v[72:73], 0
	v_mov_b64_e32 v[78:79], 0
	v_mov_b64_e32 v[80:81], 0
	v_mov_b64_e32 v[86:87], 0
	v_mov_b64_e32 v[88:89], 0
	v_mov_b64_e32 v[94:95], 0
	v_mov_b64_e32 v[96:97], 0
	v_mov_b64_e32 v[102:103], 0
	v_mov_b64_e32 v[104:105], 0
	v_mov_b64_e32 v[110:111], 0
	v_mov_b64_e32 v[112:113], 0
	v_mov_b64_e32 v[118:119], 0
	v_mov_b64_e32 v[120:121], 0
	v_mov_b64_e32 v[126:127], 0
	v_mov_b64_e32 v[128:129], 0
	s_cmpk_gt_u32 s36, 0xff
	s_cbranch_scc0 .LBB0_881
	s_cmp_gt_u32 s49, 1
	s_cbranch_scc0 .LBB0_881
	s_barrier

; __device__ __forceinline__ unsigned pk2(float lo, float hi) { unsigned r; asm("v_cvt_pk_bf16_f32 %0, %1, %2" : "=v"(r) : "v"(lo), "v"(hi)); return r; }
; __device__ __forceinline__ float silu_f(float v) { return v * __builtin_amdgcn_rcpf(1.f + __expf(-v)); }
;     __device__ __forceinline__ void operator()(const Acc& acc, const Unit& u, int wr, int wc, int fr, int fq) const {
;         const int row0 = u.pm * BM + wr * 64 + fr, col0 = u.pn * HALF + wc * 32 + 8 * fq;
; #pragma unroll
;         for (int ai = 0; ai < 2; ++ai)
; #pragma unroll
;             for (int m = 0; m < 4; ++m) { bf16_t* rp = Hd + (size_t)(row0 + ai * HALF + m * 16) * DFF + col0;
;                 float h[8];
; #pragma unroll
;                 for (int n = 0; n < 2; ++n)
; #pragma unroll
;                     for (int e = 0; e < 4; ++e) { const float g = acc[ai][0][m][n][e], up = acc[ai][1][m][n][e]; h[4 * n + e] = silu_f(g) * up; }
;                 u32x4 o; o.x = pk2(h[0], h[1]); o.y = pk2(h[2], h[3]); o.z = pk2(h[4], h[5]); o.w = pk2(h[6], h[7]);
;                 *(u32x4*)rp = o; }
.Lgx_a_pre:
	v_mul_f32_e32 v147, 0xbfb8aa3b, v126
	v_exp_f32_e32 v147, v147
	v_readlane_b32 s2, v250, 43
	v_lshl_or_b32 v148, s52, 7, v144
	v_readlane_b32 s3, v250, 44
	v_add_f32_e32 v147, 1.0, v147
	v_rcp_f32_e32 v147, v147
	v_lshl_add_u32 v146, s12, 8, v142
	v_ashrrev_i32_e32 v149, 31, v148
	v_mov_b64_e32 v[140:141], s[2:3]
	v_mul_f32_e32 v126, v126, v147
	v_mul_f32_e32 v122, v126, v122
	v_mul_f32_e32 v126, 0xbfb8aa3b, v127
	v_exp_f32_e32 v126, v126
	s_movk_i32 s2, 0x1c00
	v_mad_i64_i32 v[150:151], s[14:15], v146, s2, v[140:141]
	v_add_f32_e32 v126, 1.0, v126
	v_rcp_f32_e32 v126, v126
	v_readlane_b32 s54, v253, 13
	s_and_b64 vcc, exec, s[0:1]
	s_mov_b32 s52, s4
	v_mul_f32_e32 v126, v127, v126
	v_mul_f32_e32 v123, v126, v123
	v_mul_f32_e32 v126, 0xbfb8aa3b, v128
	v_exp_f32_e32 v126, v126
	s_mov_b32 s12, s6
	s_mov_b64 s[16:17], s[10:11]
	v_readlane_b32 s55, v253, 14
	v_add_f32_e32 v126, 1.0, v126
	v_rcp_f32_e32 v126, v126
	s_nop 0
	v_mul_f32_e32 v126, v128, v126
	v_mul_f32_e32 v124, v126, v124
	v_mul_f32_e32 v126, 0xbfb8aa3b, v129
	v_exp_f32_e32 v126, v126
	s_nop 0
	v_add_f32_e32 v126, 1.0, v126
	v_rcp_f32_e32 v126, v126
	s_nop 0
	v_mul_f32_e32 v126, v129, v126
	v_mul_f32_e32 v125, v126, v125
	v_mul_f32_e32 v126, 0xbfb8aa3b, v118
	v_exp_f32_e32 v126, v126
	s_nop 0
	v_add_f32_e32 v126, 1.0, v126
	v_rcp_f32_e32 v126, v126
	s_nop 0
	v_mul_f32_e32 v118, v118, v126
	v_mul_f32_e32 v118, v118, v114
	v_mul_f32_e32 v114, 0xbfb8aa3b, v119
	v_exp_f32_e32 v114, v114
	s_nop 0
	v_add_f32_e32 v114, 1.0, v114
	v_rcp_f32_e32 v114, v114
	s_nop 0
	v_mul_f32_e32 v114, v119, v114
	v_mul_f32_e32 v119, v114, v115
	v_mul_f32_e32 v114, 0xbfb8aa3b, v120
	v_exp_f32_e32 v114, v114
	v_cvt_pk_bf16_f32 v118, v118, v119
	s_nop 0
	v_add_f32_e32 v114, 1.0, v114
	v_rcp_f32_e32 v114, v114
	s_nop 0
	v_mul_f32_e32 v114, v120, v114
	v_mul_f32_e32 v126, v114, v116
	v_mul_f32_e32 v114, 0xbfb8aa3b, v121
	v_exp_f32_e32 v114, v114
	v_cvt_pk_bf16_f32 v116, v122, v123
	s_nop 0
	v_add_f32_e32 v114, 1.0, v114
	v_rcp_f32_e32 v114, v114
	s_nop 0
	v_mul_f32_e32 v114, v121, v114
	v_mul_f32_e32 v127, v114, v117
	v_lshlrev_b64 v[114:115], 1, v[148:149]
	v_lshl_add_u64 v[120:121], v[150:151], 0, v[114:115]
	v_cvt_pk_bf16_f32 v117, v124, v125
	v_cvt_pk_bf16_f32 v119, v126, v127
	global_store_dwordx4 v[120:121], v[116:119], off
	s_nop 1
	v_mul_f32_e32 v118, 0xbfb8aa3b, v110
	v_exp_f32_e32 v118, v118
	v_or_b32_e32 v116, 16, v146
	v_mad_i64_i32 v[116:117], s[14:15], v116, s2, v[140:141]
	v_add_f32_e32 v118, 1.0, v118
	v_rcp_f32_e32 v118, v118
	s_nop 0
	v_mul_f32_e32 v110, v110, v118
	v_mul_f32_e32 v106, v110, v106
	v_mul_f32_e32 v110, 0xbfb8aa3b, v111
	v_exp_f32_e32 v110, v110
	s_nop 0
	v_add_f32_e32 v110, 1.0, v110
	v_rcp_f32_e32 v110, v110
	s_nop 0
	v_mul_f32_e32 v110, v111, v110
	v_mul_f32_e32 v107, v110, v107
	v_mul_f32_e32 v110, 0xbfb8aa3b, v112
	v_exp_f32_e32 v110, v110
	s_nop 0
	v_add_f32_e32 v110, 1.0, v110
	v_rcp_f32_e32 v110, v110
	s_nop 0
	v_mul_f32_e32 v110, v112, v110
	v_mul_f32_e32 v108, v110, v108
	v_mul_f32_e32 v110, 0xbfb8aa3b, v113
	v_exp_f32_e32 v110, v110
	s_nop 0
	v_add_f32_e32 v110, 1.0, v110
	v_rcp_f32_e32 v110, v110
	s_nop 0
	v_mul_f32_e32 v110, v113, v110
	v_mul_f32_e32 v109, v110, v109
	v_mul_f32_e32 v110, 0xbfb8aa3b, v102
	v_exp_f32_e32 v110, v110
	s_nop 0
	v_add_f32_e32 v110, 1.0, v110
	v_rcp_f32_e32 v110, v110
	s_nop 0
	v_mul_f32_e32 v102, v102, v110
	v_mul_f32_e32 v110, v102, v98
	v_mul_f32_e32 v98, 0xbfb8aa3b, v103
	v_exp_f32_e32 v98, v98
	s_nop 0
	v_add_f32_e32 v98, 1.0, v98
	v_rcp_f32_e32 v98, v98
	s_nop 0
	v_mul_f32_e32 v98, v103, v98
	v_mul_f32_e32 v111, v98, v99
	v_mul_f32_e32 v98, 0xbfb8aa3b, v104
	v_exp_f32_e32 v98, v98
	v_lshl_add_u64 v[102:103], v[116:117], 0, v[114:115]
	v_cvt_pk_bf16_f32 v99, v108, v109
	v_add_f32_e32 v98, 1.0, v98
	v_rcp_f32_e32 v98, v98
	s_nop 0
	v_mul_f32_e32 v98, v104, v98
	v_mul_f32_e32 v104, v98, v100
	v_mul_f32_e32 v98, 0xbfb8aa3b, v105
	v_exp_f32_e32 v98, v98
	v_cvt_pk_bf16_f32 v100, v110, v111
	s_nop 0
	v_add_f32_e32 v98, 1.0, v98
	v_rcp_f32_e32 v98, v98
	s_nop 0
	v_mul_f32_e32 v98, v105, v98
	v_mul_f32_e32 v101, v98, v101
	v_cvt_pk_bf16_f32 v98, v106, v107
	v_cvt_pk_bf16_f32 v101, v104, v101
	global_store_dwordx4 v[102:103], v[98:101], off
	s_nop 1
	v_mul_f32_e32 v100, 0xbfb8aa3b, v94
	v_exp_f32_e32 v100, v100
	v_or_b32_e32 v98, 32, v146
	v_mad_i64_i32 v[98:99], s[14:15], v98, s2, v[140:141]
	v_add_f32_e32 v100, 1.0, v100
	v_rcp_f32_e32 v100, v100
	s_nop 0
	v_mul_f32_e32 v94, v94, v100
	v_mul_f32_e32 v90, v94, v90
	v_mul_f32_e32 v94, 0xbfb8aa3b, v95
	v_exp_f32_e32 v94, v94
	s_nop 0
	v_add_f32_e32 v94, 1.0, v94
	v_rcp_f32_e32 v94, v94
	s_nop 0
	v_mul_f32_e32 v94, v95, v94
	v_mul_f32_e32 v91, v94, v91
	v_mul_f32_e32 v94, 0xbfb8aa3b, v96
	v_exp_f32_e32 v94, v94
	s_nop 0
	v_add_f32_e32 v94, 1.0, v94
	v_rcp_f32_e32 v94, v94
	s_nop 0
	v_mul_f32_e32 v94, v96, v94
	v_mul_f32_e32 v92, v94, v92
	v_mul_f32_e32 v94, 0xbfb8aa3b, v97
	v_exp_f32_e32 v94, v94
	s_nop 0
	v_add_f32_e32 v94, 1.0, v94
	v_rcp_f32_e32 v94, v94
	s_nop 0
	v_mul_f32_e32 v94, v97, v94
	v_mul_f32_e32 v93, v94, v93
	v_mul_f32_e32 v94, 0xbfb8aa3b, v86
	v_exp_f32_e32 v94, v94
	s_nop 0
	v_add_f32_e32 v94, 1.0, v94
	v_rcp_f32_e32 v94, v94
	s_nop 0
	v_mul_f32_e32 v86, v86, v94
	v_mul_f32_e32 v94, v86, v82
	v_mul_f32_e32 v82, 0xbfb8aa3b, v87
	v_exp_f32_e32 v82, v82
	s_nop 0
	v_add_f32_e32 v82, 1.0, v82
	v_rcp_f32_e32 v82, v82
	s_nop 0
	v_mul_f32_e32 v82, v87, v82
	v_mul_f32_e32 v95, v82, v83
	v_mul_f32_e32 v82, 0xbfb8aa3b, v88
	v_exp_f32_e32 v82, v82
	v_lshl_add_u64 v[86:87], v[98:99], 0, v[114:115]
	v_cvt_pk_bf16_f32 v83, v92, v93
	v_add_f32_e32 v82, 1.0, v82
	v_rcp_f32_e32 v82, v82
; __device__ __forceinline__ unsigned pk2(float lo, float hi) { unsigned r; asm("v_cvt_pk_bf16_f32 %0, %1, %2" : "=v"(r) : "v"(lo), "v"(hi)); return r; }
; __device__ __forceinline__ float silu_f(float v) { return v * __builtin_amdgcn_rcpf(1.f + __expf(-v)); }
;     __device__ __forceinline__ void operator()(const Acc& acc, const Unit& u, int wr, int wc, int fr, int fq) const {
;         const int row0 = u.pm * BM + wr * 64 + fr, col0 = u.pn * HALF + wc * 32 + 8 * fq;
; #pragma unroll
;         for (int ai = 0; ai < 2; ++ai)
; #pragma unroll
;             for (int m = 0; m < 4; ++m) { bf16_t* rp = Hd + (size_t)(row0 + ai * HALF + m * 16) * DFF + col0;
;                 float h[8];
; #pragma unroll
;                 for (int n = 0; n < 2; ++n)
; #pragma unroll
;                     for (int e = 0; e < 4; ++e) { const float g = acc[ai][0][m][n][e], up = acc[ai][1][m][n][e]; h[4 * n + e] = silu_f(g) * up; }
;                 u32x4 o; o.x = pk2(h[0], h[1]); o.y = pk2(h[2], h[3]); o.z = pk2(h[4], h[5]); o.w = pk2(h[6], h[7]);
;                 *(u32x4*)rp = o; }
	s_nop 0
	v_mul_f32_e32 v82, v88, v82
	v_mul_f32_e32 v88, v82, v84
	v_mul_f32_e32 v82, 0xbfb8aa3b, v89
	v_exp_f32_e32 v82, v82
	v_cvt_pk_bf16_f32 v84, v94, v95
	s_nop 0
	v_add_f32_e32 v82, 1.0, v82
	v_rcp_f32_e32 v82, v82
	s_nop 0
	v_mul_f32_e32 v82, v89, v82
	v_mul_f32_e32 v85, v82, v85
	v_cvt_pk_bf16_f32 v82, v90, v91
	v_cvt_pk_bf16_f32 v85, v88, v85
	global_store_dwordx4 v[86:87], v[82:85], off
	s_nop 1
	v_mul_f32_e32 v84, 0xbfb8aa3b, v78
	v_exp_f32_e32 v84, v84
	v_or_b32_e32 v82, 48, v146
	v_mad_i64_i32 v[82:83], s[14:15], v82, s2, v[140:141]
	v_add_f32_e32 v84, 1.0, v84
	v_rcp_f32_e32 v84, v84
	s_nop 0
	v_mul_f32_e32 v78, v78, v84
	v_mul_f32_e32 v74, v78, v74
	v_mul_f32_e32 v78, 0xbfb8aa3b, v79
	v_exp_f32_e32 v78, v78
	s_nop 0
	v_add_f32_e32 v78, 1.0, v78
	v_rcp_f32_e32 v78, v78
	s_nop 0
	v_mul_f32_e32 v78, v79, v78
	v_mul_f32_e32 v75, v78, v75
	v_mul_f32_e32 v78, 0xbfb8aa3b, v80
	v_exp_f32_e32 v78, v78
	s_nop 0
	v_add_f32_e32 v78, 1.0, v78
	v_rcp_f32_e32 v78, v78
	s_nop 0
	v_mul_f32_e32 v78, v80, v78
	v_mul_f32_e32 v76, v78, v76
	v_mul_f32_e32 v78, 0xbfb8aa3b, v81
	v_exp_f32_e32 v78, v78
	s_nop 0
	v_add_f32_e32 v78, 1.0, v78
	v_rcp_f32_e32 v78, v78
	s_nop 0
	v_mul_f32_e32 v78, v81, v78
	v_mul_f32_e32 v77, v78, v77
	v_mul_f32_e32 v78, 0xbfb8aa3b, v70
	v_exp_f32_e32 v78, v78
	s_nop 0
	v_add_f32_e32 v78, 1.0, v78
	v_rcp_f32_e32 v78, v78
	s_nop 0
	v_mul_f32_e32 v70, v70, v78
	v_mul_f32_e32 v78, v70, v66
	v_mul_f32_e32 v66, 0xbfb8aa3b, v71
	v_exp_f32_e32 v66, v66
	s_nop 0
	v_add_f32_e32 v66, 1.0, v66
	v_rcp_f32_e32 v66, v66
	s_nop 0
	v_mul_f32_e32 v66, v71, v66
	v_mul_f32_e32 v79, v66, v67
	v_mul_f32_e32 v66, 0xbfb8aa3b, v72
	v_exp_f32_e32 v66, v66
	v_lshl_add_u64 v[70:71], v[82:83], 0, v[114:115]
	v_cvt_pk_bf16_f32 v67, v76, v77
	v_add_f32_e32 v66, 1.0, v66
	v_rcp_f32_e32 v66, v66
	s_nop 0
	v_mul_f32_e32 v66, v72, v66
	v_mul_f32_e32 v72, v66, v68
	v_mul_f32_e32 v66, 0xbfb8aa3b, v73
	v_exp_f32_e32 v66, v66
	v_cvt_pk_bf16_f32 v68, v78, v79
	s_nop 0
	v_add_f32_e32 v66, 1.0, v66
	v_rcp_f32_e32 v66, v66
	s_nop 0
	v_mul_f32_e32 v66, v73, v66
	v_mul_f32_e32 v69, v66, v69
	v_cvt_pk_bf16_f32 v66, v74, v75
	v_cvt_pk_bf16_f32 v69, v72, v69
	global_store_dwordx4 v[70:71], v[66:69], off
	s_nop 1
	v_mul_f32_e32 v68, 0xbfb8aa3b, v62
	v_exp_f32_e32 v68, v68
	v_add_u32_e32 v66, 0x80, v146
	v_mad_i64_i32 v[66:67], s[14:15], v66, s2, v[140:141]
	v_add_f32_e32 v68, 1.0, v68
	v_rcp_f32_e32 v68, v68
	s_nop 0
	v_mul_f32_e32 v62, v62, v68
	v_mul_f32_e32 v58, v62, v58
	v_mul_f32_e32 v62, 0xbfb8aa3b, v63
	v_exp_f32_e32 v62, v62
	s_nop 0
	v_add_f32_e32 v62, 1.0, v62
	v_rcp_f32_e32 v62, v62
	s_nop 0
	v_mul_f32_e32 v62, v63, v62
	v_mul_f32_e32 v59, v62, v59
	v_mul_f32_e32 v62, 0xbfb8aa3b, v64
	v_exp_f32_e32 v62, v62
	s_nop 0
	v_add_f32_e32 v62, 1.0, v62
	v_rcp_f32_e32 v62, v62
	s_nop 0
	v_mul_f32_e32 v62, v64, v62
	v_mul_f32_e32 v60, v62, v60
	v_mul_f32_e32 v62, 0xbfb8aa3b, v65
	v_exp_f32_e32 v62, v62
	s_nop 0
	v_add_f32_e32 v62, 1.0, v62
	v_rcp_f32_e32 v62, v62
	s_nop 0
	v_mul_f32_e32 v62, v65, v62
	v_mul_f32_e32 v61, v62, v61
	v_mul_f32_e32 v62, 0xbfb8aa3b, v54
	v_exp_f32_e32 v62, v62
	s_nop 0
	v_add_f32_e32 v62, 1.0, v62
	v_rcp_f32_e32 v62, v62
	s_nop 0
	v_mul_f32_e32 v54, v54, v62
	v_mul_f32_e32 v62, v54, v50
	v_mul_f32_e32 v50, 0xbfb8aa3b, v55
	v_exp_f32_e32 v50, v50
	s_nop 0
	v_add_f32_e32 v50, 1.0, v50
	v_rcp_f32_e32 v50, v50
	s_nop 0
	v_mul_f32_e32 v50, v55, v50
	v_mul_f32_e32 v63, v50, v51
	v_mul_f32_e32 v50, 0xbfb8aa3b, v56
	v_exp_f32_e32 v50, v50
	v_lshl_add_u64 v[54:55], v[66:67], 0, v[114:115]
	v_cvt_pk_bf16_f32 v51, v60, v61
	v_add_f32_e32 v50, 1.0, v50
	v_rcp_f32_e32 v50, v50
	s_nop 0
	v_mul_f32_e32 v50, v56, v50
	v_mul_f32_e32 v56, v50, v52
	v_mul_f32_e32 v50, 0xbfb8aa3b, v57
	v_exp_f32_e32 v50, v50
	v_cvt_pk_bf16_f32 v52, v62, v63
	s_nop 0
	v_add_f32_e32 v50, 1.0, v50
	v_rcp_f32_e32 v50, v50
	s_nop 0
	v_mul_f32_e32 v50, v57, v50
	v_mul_f32_e32 v53, v50, v53
	v_cvt_pk_bf16_f32 v50, v58, v59
	v_cvt_pk_bf16_f32 v53, v56, v53
	global_store_dwordx4 v[54:55], v[50:53], off
	s_nop 1
	v_mul_f32_e32 v52, 0xbfb8aa3b, v46
	v_exp_f32_e32 v52, v52
	v_add_u32_e32 v50, 0x90, v146
	v_mad_i64_i32 v[50:51], s[14:15], v50, s2, v[140:141]
	v_add_f32_e32 v52, 1.0, v52
	v_rcp_f32_e32 v52, v52
	s_nop 0
	v_mul_f32_e32 v46, v46, v52
	v_mul_f32_e32 v42, v46, v42
	v_mul_f32_e32 v46, 0xbfb8aa3b, v47
	v_exp_f32_e32 v46, v46
	s_nop 0
	v_add_f32_e32 v46, 1.0, v46
	v_rcp_f32_e32 v46, v46
	s_nop 0
	v_mul_f32_e32 v46, v47, v46
	v_mul_f32_e32 v43, v46, v43
	v_mul_f32_e32 v46, 0xbfb8aa3b, v48
	v_exp_f32_e32 v46, v46
	s_nop 0
	v_add_f32_e32 v46, 1.0, v46
	v_rcp_f32_e32 v46, v46
	s_nop 0
	v_mul_f32_e32 v46, v48, v46
	v_mul_f32_e32 v44, v46, v44
	v_mul_f32_e32 v46, 0xbfb8aa3b, v49
	v_exp_f32_e32 v46, v46
; __device__ __forceinline__ unsigned pk2(float lo, float hi) { unsigned r; asm("v_cvt_pk_bf16_f32 %0, %1, %2" : "=v"(r) : "v"(lo), "v"(hi)); return r; }
; __device__ __forceinline__ float silu_f(float v) { return v * __builtin_amdgcn_rcpf(1.f + __expf(-v)); }
; template <class Epi, class Sched>
; __device__ __forceinline__ void gemm_phase(LAS unsigned char* lds, const int K, const int lda, const int ldb, const Sched& S, const Epi& E) {
;     ...
;         if constexpr (!Epi::AFTER_DRAIN) E(acc, cur, wr, wc, fr, fq);
;         if (!has_next) break;
;     __device__ __forceinline__ void operator()(const Acc& acc, const Unit& u, int wr, int wc, int fr, int fq) const {
;         const int row0 = u.pm * BM + wr * 64 + fr, col0 = u.pn * HALF + wc * 32 + 8 * fq;
; #pragma unroll
;         for (int ai = 0; ai < 2; ++ai)
; #pragma unroll
;             for (int m = 0; m < 4; ++m) { bf16_t* rp = Hd + (size_t)(row0 + ai * HALF + m * 16) * DFF + col0;
;                 float h[8];
; #pragma unroll
;                 for (int n = 0; n < 2; ++n)
; #pragma unroll
;                     for (int e = 0; e < 4; ++e) { const float g = acc[ai][0][m][n][e], up = acc[ai][1][m][n][e]; h[4 * n + e] = silu_f(g) * up; }
;                 u32x4 o; o.x = pk2(h[0], h[1]); o.y = pk2(h[2], h[3]); o.z = pk2(h[4], h[5]); o.w = pk2(h[6], h[7]);
;                 *(u32x4*)rp = o; }
	s_nop 0
	v_add_f32_e32 v46, 1.0, v46
	v_rcp_f32_e32 v46, v46
	s_nop 0
	v_mul_f32_e32 v46, v49, v46
	v_mul_f32_e32 v45, v46, v45
	v_mul_f32_e32 v46, 0xbfb8aa3b, v38
	v_exp_f32_e32 v46, v46
	s_nop 0
	v_add_f32_e32 v46, 1.0, v46
	v_rcp_f32_e32 v46, v46
	s_nop 0
	v_mul_f32_e32 v38, v38, v46
	v_mul_f32_e32 v46, v38, v34
	v_mul_f32_e32 v34, 0xbfb8aa3b, v39
	v_exp_f32_e32 v34, v34
	s_nop 0
	v_add_f32_e32 v34, 1.0, v34
	v_rcp_f32_e32 v34, v34
	s_nop 0
	v_mul_f32_e32 v34, v39, v34
	v_mul_f32_e32 v47, v34, v35
	v_mul_f32_e32 v34, 0xbfb8aa3b, v40
	v_exp_f32_e32 v34, v34
	v_lshl_add_u64 v[38:39], v[50:51], 0, v[114:115]
	v_cvt_pk_bf16_f32 v35, v44, v45
	v_add_f32_e32 v34, 1.0, v34
	v_rcp_f32_e32 v34, v34
	s_nop 0
	v_mul_f32_e32 v34, v40, v34
	v_mul_f32_e32 v40, v34, v36
	v_mul_f32_e32 v34, 0xbfb8aa3b, v41
	v_exp_f32_e32 v34, v34
	v_cvt_pk_bf16_f32 v36, v46, v47
	s_nop 0
	v_add_f32_e32 v34, 1.0, v34
	v_rcp_f32_e32 v34, v34
	s_nop 0
	v_mul_f32_e32 v34, v41, v34
	v_mul_f32_e32 v37, v34, v37
	v_cvt_pk_bf16_f32 v34, v42, v43
	v_cvt_pk_bf16_f32 v37, v40, v37
	global_store_dwordx4 v[38:39], v[34:37], off
	s_nop 1
	v_mul_f32_e32 v36, 0xbfb8aa3b, v30
	v_exp_f32_e32 v36, v36
	v_add_u32_e32 v34, 0xa0, v146
	v_mad_i64_i32 v[34:35], s[14:15], v34, s2, v[140:141]
	v_add_f32_e32 v36, 1.0, v36
	v_rcp_f32_e32 v36, v36
	s_nop 0
	v_mul_f32_e32 v30, v30, v36
	v_mul_f32_e32 v26, v30, v26
	v_mul_f32_e32 v30, 0xbfb8aa3b, v31
	v_exp_f32_e32 v30, v30
	s_nop 0
	v_add_f32_e32 v30, 1.0, v30
	v_rcp_f32_e32 v30, v30
	s_nop 0
	v_mul_f32_e32 v30, v31, v30
	v_mul_f32_e32 v27, v30, v27
	v_mul_f32_e32 v30, 0xbfb8aa3b, v32
	v_exp_f32_e32 v30, v30
	s_nop 0
	v_add_f32_e32 v30, 1.0, v30
	v_rcp_f32_e32 v30, v30
	s_nop 0
	v_mul_f32_e32 v30, v32, v30
	v_mul_f32_e32 v28, v30, v28
	v_mul_f32_e32 v30, 0xbfb8aa3b, v33
	v_exp_f32_e32 v30, v30
	s_nop 0
	v_add_f32_e32 v30, 1.0, v30
	v_rcp_f32_e32 v30, v30
	s_nop 0
	v_mul_f32_e32 v30, v33, v30
	v_mul_f32_e32 v29, v30, v29
	v_mul_f32_e32 v30, 0xbfb8aa3b, v22
	v_exp_f32_e32 v30, v30
	s_nop 0
	v_add_f32_e32 v30, 1.0, v30
	v_rcp_f32_e32 v30, v30
	s_nop 0
	v_mul_f32_e32 v22, v22, v30
	v_mul_f32_e32 v30, v22, v18
	v_mul_f32_e32 v18, 0xbfb8aa3b, v23
	v_exp_f32_e32 v18, v18
	s_nop 0
	v_add_f32_e32 v18, 1.0, v18
	v_rcp_f32_e32 v18, v18
	s_nop 0
	v_mul_f32_e32 v18, v23, v18
	v_mul_f32_e32 v31, v18, v19
	v_mul_f32_e32 v18, 0xbfb8aa3b, v24
	v_exp_f32_e32 v18, v18
	v_lshl_add_u64 v[22:23], v[34:35], 0, v[114:115]
	v_cvt_pk_bf16_f32 v19, v28, v29
	v_add_f32_e32 v18, 1.0, v18
	v_rcp_f32_e32 v18, v18
	s_nop 0
	v_mul_f32_e32 v18, v24, v18
	v_mul_f32_e32 v24, v18, v20
	v_mul_f32_e32 v18, 0xbfb8aa3b, v25
	v_exp_f32_e32 v18, v18
	v_cvt_pk_bf16_f32 v20, v30, v31
	s_nop 0
	v_add_f32_e32 v18, 1.0, v18
	v_rcp_f32_e32 v18, v18
	s_nop 0
	v_mul_f32_e32 v18, v25, v18
	v_mul_f32_e32 v21, v18, v21
	v_cvt_pk_bf16_f32 v18, v26, v27
	v_cvt_pk_bf16_f32 v21, v24, v21
	global_store_dwordx4 v[22:23], v[18:21], off
	s_nop 1
	v_mul_f32_e32 v20, 0xbfb8aa3b, v14
	v_exp_f32_e32 v20, v20
	v_add_u32_e32 v18, 0xb0, v146
	v_mad_i64_i32 v[18:19], s[14:15], v18, s2, v[140:141]
	v_add_f32_e32 v20, 1.0, v20
	v_rcp_f32_e32 v20, v20
	s_mov_b64 s[14:15], s[8:9]
	v_mul_f32_e32 v14, v14, v20
	v_mul_f32_e32 v10, v14, v10
	v_mul_f32_e32 v14, 0xbfb8aa3b, v15
	v_exp_f32_e32 v14, v14
	s_nop 0
	v_add_f32_e32 v14, 1.0, v14
	v_rcp_f32_e32 v14, v14
	s_nop 0
	v_mul_f32_e32 v14, v15, v14
	v_mul_f32_e32 v11, v14, v11
	v_mul_f32_e32 v14, 0xbfb8aa3b, v16
	v_exp_f32_e32 v14, v14
	s_nop 0
	v_add_f32_e32 v14, 1.0, v14
	v_rcp_f32_e32 v14, v14
	s_nop 0
	v_mul_f32_e32 v14, v16, v14
	v_mul_f32_e32 v12, v14, v12
	v_mul_f32_e32 v14, 0xbfb8aa3b, v17
	v_exp_f32_e32 v14, v14
	s_nop 0
	v_add_f32_e32 v14, 1.0, v14
	v_rcp_f32_e32 v14, v14
	s_nop 0
	v_mul_f32_e32 v14, v17, v14
	v_mul_f32_e32 v13, v14, v13
	v_mul_f32_e32 v14, 0xbfb8aa3b, v6
	v_exp_f32_e32 v14, v14
	s_nop 0
	v_add_f32_e32 v14, 1.0, v14
	v_rcp_f32_e32 v14, v14
	s_nop 0
	v_mul_f32_e32 v6, v6, v14
	v_mul_f32_e32 v14, v6, v2
	v_mul_f32_e32 v2, 0xbfb8aa3b, v7
	v_exp_f32_e32 v2, v2
	s_nop 0
	v_add_f32_e32 v2, 1.0, v2
	v_rcp_f32_e32 v2, v2
	s_nop 0
	v_mul_f32_e32 v2, v7, v2
	v_mul_f32_e32 v15, v2, v3
	v_mul_f32_e32 v2, 0xbfb8aa3b, v8
	v_exp_f32_e32 v2, v2
	v_lshl_add_u64 v[6:7], v[18:19], 0, v[114:115]
	v_cvt_pk_bf16_f32 v3, v12, v13
	v_add_f32_e32 v2, 1.0, v2
	v_rcp_f32_e32 v2, v2
	s_nop 0
	v_mul_f32_e32 v2, v8, v2
	v_mul_f32_e32 v8, v2, v4
	v_mul_f32_e32 v2, 0xbfb8aa3b, v9
	v_exp_f32_e32 v2, v2
	v_cvt_pk_bf16_f32 v4, v14, v15
	s_nop 0
	v_add_f32_e32 v2, 1.0, v2
	v_rcp_f32_e32 v2, v2
	s_nop 0
	v_mul_f32_e32 v2, v9, v2
	v_mul_f32_e32 v5, v2, v5
	v_cvt_pk_bf16_f32 v2, v10, v11
	v_cvt_pk_bf16_f32 v5, v8, v5
	global_store_dwordx4 v[6:7], v[2:5], off
	s_cbranch_vccz .LBB0_874
